# nt hint on the read-once residual-row loads of the four fused GEMM epilogues (f32 x in L0 out-proj, bf16 rows elsewhere)
# baseline (speedup 1.0000x reference)
.LBB0_610:
	s_or_b64 exec, exec, s[22:23]
	s_lshl_b32 s0, s17, 5
	s_lshl_b32 s1, s18, 8
	s_or_b32 s0, s1, s0
	v_lshrrev_b32_e32 v130, 2, v148
	v_and_or_b32 v162, v130, 12, s0
	s_lshl_b32 s0, s16, 5
	s_and_b32 s0, s0, 0xfffffc00
	v_add_u32_e32 v148, s0, v162
	v_readlane_b32 s0, v251, 45
	v_add_u32_e32 v150, s19, v152
	v_readlane_b32 s40, v251, 25
	v_ashrrev_i32_e32 v149, 31, v148
	v_readlane_b32 s1, v251, 46
	v_ashrrev_i32_e32 v151, 31, v150
	v_readlane_b32 s41, v251, 26
	v_lshl_add_u64 v[138:139], v[148:149], 2, s[0:1]
	v_ashrrev_i32_e32 v163, 31, v162
	v_lshlrev_b64 v[130:131], 12, v[150:151]
	s_mov_b64 s[0:1], s[40:41]
	v_lshl_add_u64 v[130:131], s[0:1], 0, v[130:131]
	v_lshlrev_b64 v[168:169], 2, v[162:163]
	s_waitcnt lgkmcnt(0)
	s_barrier
	v_lshl_add_u64 v[172:173], v[130:131], 0, v[168:169]
	global_load_dwordx4 v[154:157], v[172:173], off nt
	global_load_dwordx4 v[134:137], v[138:139], off
	s_waitcnt lgkmcnt(0)
	global_load_dwordx4 v[130:133], v[138:139], off offset:64
	global_load_dwordx4 v[158:161], v[172:173], off offset:64 nt
	global_load_dwordx4 v[164:167], v[172:173], off offset:512 nt
	global_load_dwordx4 v[142:145], v[138:139], off offset:512
	s_nop 0
	global_load_dwordx4 v[138:141], v[138:139], off offset:576
	s_nop 0
	global_load_dwordx4 v[172:175], v[172:173], off offset:576 nt
	v_lshl_add_u32 v184, v152, 3, 0
	ds_read_b64 v[176:177], v184 offset:8192
	v_add_u32_e32 v152, 16, v150
	v_ashrrev_i32_e32 v153, 31, v152
	v_lshlrev_b64 v[178:179], 12, v[152:153]
	v_lshl_add_u64 v[178:179], s[0:1], 0, v[178:179]
	s_waitcnt lgkmcnt(0)
	v_pk_mul_f32 v[126:127], v[126:127], v[176:177] op_sel:[0,1]
	v_pk_mul_f32 v[128:129], v[128:129], v[176:177] op_sel:[0,1]
	v_pk_mul_f32 v[122:123], v[122:123], v[176:177] op_sel:[0,1]
	v_pk_mul_f32 v[124:125], v[124:125], v[176:177] op_sel:[0,1]
	v_pk_mul_f32 v[180:181], v[118:119], v[176:177] op_sel:[0,1]
	v_pk_mul_f32 v[188:189], v[120:121], v[176:177] op_sel:[0,1]
	v_pk_mul_f32 v[114:115], v[114:115], v[176:177] op_sel:[0,1]
	v_pk_mul_f32 v[116:117], v[116:117], v[176:177] op_sel:[0,1]
	v_lshl_add_u64 v[178:179], v[178:179], 0, v[168:169]
	v_readlane_b32 s42, v251, 27
	v_readlane_b32 s43, v251, 28
	v_readlane_b32 s44, v251, 29
	v_readlane_b32 s45, v251, 30
	v_readlane_b32 s46, v251, 31
	v_readlane_b32 s47, v251, 32
	v_readlane_b32 s48, v251, 33
	v_readlane_b32 s49, v251, 34
	v_readlane_b32 s50, v251, 35
	v_readlane_b32 s51, v251, 36
	v_readlane_b32 s52, v251, 37
	v_readlane_b32 s53, v251, 38
	v_readlane_b32 s54, v251, 39
	v_readlane_b32 s55, v251, 40
	s_waitcnt vmcnt(0)
	v_pk_fma_f32 v[120:121], v[136:137], v[128:129], v[156:157]
	v_pk_fma_f32 v[118:119], v[134:135], v[126:127], v[154:155]
	v_pk_fma_f32 v[124:125], v[132:133], v[124:125], v[160:161]
	v_pk_fma_f32 v[122:123], v[130:131], v[122:123], v[158:159]
	v_pk_fma_f32 v[128:129], v[144:145], v[188:189], v[166:167]
	v_pk_fma_f32 v[126:127], v[142:143], v[180:181], v[164:165]
	v_pk_fma_f32 v[116:117], v[140:141], v[116:117], v[174:175]
	v_pk_fma_f32 v[114:115], v[138:139], v[114:115], v[172:173]
	v_add_u32_e32 v154, 32, v150
	global_load_dwordx4 v[156:159], v[178:179], off nt
	global_load_dwordx4 v[164:167], v[178:179], off offset:64 nt
	global_load_dwordx4 v[172:175], v[178:179], off offset:512 nt
	s_nop 0
	global_load_dwordx4 v[176:179], v[178:179], off offset:576 nt
	ds_read_b64 v[160:161], v184 offset:8320
	v_ashrrev_i32_e32 v155, 31, v154
	v_lshlrev_b64 v[180:181], 12, v[154:155]
	v_lshl_add_u64 v[180:181], s[0:1], 0, v[180:181]
	v_lshl_add_u64 v[180:181], v[180:181], 0, v[168:169]
	s_waitcnt lgkmcnt(0)
	v_pk_mul_f32 v[110:111], v[110:111], v[160:161] op_sel:[0,1]
	v_pk_mul_f32 v[112:113], v[112:113], v[160:161] op_sel:[0,1]
	v_pk_mul_f32 v[106:107], v[106:107], v[160:161] op_sel:[0,1]
	v_pk_mul_f32 v[108:109], v[108:109], v[160:161] op_sel:[0,1]
	v_pk_mul_f32 v[102:103], v[102:103], v[160:161] op_sel:[0,1]
	v_pk_mul_f32 v[104:105], v[104:105], v[160:161] op_sel:[0,1]
	v_pk_mul_f32 v[98:99], v[98:99], v[160:161] op_sel:[0,1]
	v_pk_mul_f32 v[100:101], v[100:101], v[160:161] op_sel:[0,1]
	v_mov_b32_e32 v196, v118
	v_mov_b32_e32 v197, v121
	v_mov_b32_e32 v204, v123
	v_mov_b32_e32 v205, v124
	v_mov_b32_e32 v206, v122
	v_mov_b32_e32 v207, v125
	v_add_f32_e32 v209, v126, v127
	v_add_f32_e32 v213, v128, v129
	v_mov_b32_e32 v208, v114
	v_mov_b32_e32 v212, v115
	v_mov_b32_e32 v214, v117
	s_waitcnt vmcnt(3)
	v_pk_fma_f32 v[112:113], v[136:137], v[112:113], v[158:159]
	v_pk_fma_f32 v[110:111], v[134:135], v[110:111], v[156:157]
	s_waitcnt vmcnt(2)
	v_pk_fma_f32 v[108:109], v[132:133], v[108:109], v[166:167]
	v_pk_fma_f32 v[106:107], v[130:131], v[106:107], v[164:165]
	s_waitcnt vmcnt(1)
	v_pk_fma_f32 v[104:105], v[144:145], v[104:105], v[174:175]
	v_pk_fma_f32 v[102:103], v[142:143], v[102:103], v[172:173]
	s_waitcnt vmcnt(0)
	v_pk_fma_f32 v[100:101], v[140:141], v[100:101], v[178:179]
	v_pk_fma_f32 v[98:99], v[138:139], v[98:99], v[176:177]
	v_add_u32_e32 v156, 48, v150
	global_load_dwordx4 v[158:161], v[180:181], off nt
	global_load_dwordx4 v[164:167], v[180:181], off offset:64 nt
	global_load_dwordx4 v[172:175], v[180:181], off offset:512 nt
	global_load_dwordx4 v[176:179], v[180:181], off offset:576 nt
	ds_read_b64 v[180:181], v184 offset:8448
	v_ashrrev_i32_e32 v157, 31, v156
	v_lshlrev_b64 v[188:189], 12, v[156:157]
	v_lshl_add_u64 v[188:189], s[0:1], 0, v[188:189]
	v_lshl_add_u64 v[188:189], v[188:189], 0, v[168:169]
	s_waitcnt lgkmcnt(0)
	v_pk_mul_f32 v[94:95], v[94:95], v[180:181] op_sel:[0,1]
	v_pk_mul_f32 v[96:97], v[96:97], v[180:181] op_sel:[0,1]
	v_pk_mul_f32 v[90:91], v[90:91], v[180:181] op_sel:[0,1]
	v_pk_mul_f32 v[92:93], v[92:93], v[180:181] op_sel:[0,1]
	v_pk_mul_f32 v[86:87], v[86:87], v[180:181] op_sel:[0,1]
	v_pk_mul_f32 v[88:89], v[88:89], v[180:181] op_sel:[0,1]
	v_pk_mul_f32 v[82:83], v[82:83], v[180:181] op_sel:[0,1]
	v_pk_mul_f32 v[84:85], v[84:85], v[180:181] op_sel:[0,1]
	s_waitcnt vmcnt(3)
	v_pk_fma_f32 v[96:97], v[136:137], v[96:97], v[160:161]
	v_pk_fma_f32 v[94:95], v[134:135], v[94:95], v[158:159]
	s_waitcnt vmcnt(2)
	v_pk_fma_f32 v[92:93], v[132:133], v[92:93], v[166:167]
	v_pk_fma_f32 v[90:91], v[130:131], v[90:91], v[164:165]
	s_waitcnt vmcnt(1)
	v_pk_fma_f32 v[88:89], v[144:145], v[88:89], v[174:175]
	v_pk_fma_f32 v[86:87], v[142:143], v[86:87], v[172:173]
	s_waitcnt vmcnt(0)
	v_pk_fma_f32 v[84:85], v[140:141], v[84:85], v[178:179]
	v_pk_fma_f32 v[82:83], v[138:139], v[82:83], v[176:177]
	v_add_u32_e32 v158, 0x80, v150
	global_load_dwordx4 v[164:167], v[188:189], off nt
	global_load_dwordx4 v[172:175], v[188:189], off offset:64 nt
	global_load_dwordx4 v[176:179], v[188:189], off offset:512 nt
	s_nop 0
	global_load_dwordx4 v[188:191], v[188:189], off offset:576 nt
	ds_read_b64 v[160:161], v184 offset:8576
	v_ashrrev_i32_e32 v159, 31, v158
	v_lshlrev_b64 v[180:181], 12, v[158:159]
	v_lshl_add_u64 v[180:181], s[0:1], 0, v[180:181]
	v_lshl_add_u64 v[180:181], v[180:181], 0, v[168:169]
	s_waitcnt lgkmcnt(0)
	v_pk_mul_f32 v[78:79], v[78:79], v[160:161] op_sel:[0,1]
	v_pk_mul_f32 v[80:81], v[80:81], v[160:161] op_sel:[0,1]
	v_pk_mul_f32 v[74:75], v[74:75], v[160:161] op_sel:[0,1]
	v_pk_mul_f32 v[76:77], v[76:77], v[160:161] op_sel:[0,1]
	v_pk_mul_f32 v[70:71], v[70:71], v[160:161] op_sel:[0,1]
	v_pk_mul_f32 v[72:73], v[72:73], v[160:161] op_sel:[0,1]
	v_pk_mul_f32 v[66:67], v[66:67], v[160:161] op_sel:[0,1]
	v_pk_mul_f32 v[68:69], v[68:69], v[160:161] op_sel:[0,1]
	v_add_u32_e32 v160, 0x90, v150
	v_ashrrev_i32_e32 v161, 31, v160
	v_lshlrev_b64 v[192:193], 12, v[160:161]
	v_lshl_add_u64 v[192:193], s[0:1], 0, v[192:193]
	v_lshl_add_u64 v[192:193], v[192:193], 0, v[168:169]
	s_waitcnt vmcnt(3)
	v_pk_fma_f32 v[80:81], v[136:137], v[80:81], v[166:167]
	v_pk_fma_f32 v[78:79], v[134:135], v[78:79], v[164:165]
	s_waitcnt vmcnt(2)
	v_pk_fma_f32 v[76:77], v[132:133], v[76:77], v[174:175]
	v_pk_fma_f32 v[74:75], v[130:131], v[74:75], v[172:173]
	s_waitcnt vmcnt(1)
	v_pk_fma_f32 v[72:73], v[144:145], v[72:73], v[178:179]
	v_pk_fma_f32 v[70:71], v[142:143], v[70:71], v[176:177]
	s_waitcnt vmcnt(0)
	v_pk_fma_f32 v[68:69], v[140:141], v[68:69], v[190:191]
	v_pk_fma_f32 v[66:67], v[138:139], v[66:67], v[188:189]
	s_nop 0
	global_load_dwordx4 v[164:167], v[180:181], off nt
	global_load_dwordx4 v[172:175], v[180:181], off offset:64 nt
	global_load_dwordx4 v[176:179], v[180:181], off offset:512 nt
	global_load_dwordx4 v[188:191], v[180:181], off offset:576 nt
	ds_read_b64 v[180:181], v184 offset:9216
	s_waitcnt lgkmcnt(0)
	v_pk_mul_f32 v[62:63], v[62:63], v[180:181] op_sel:[0,1]
	v_pk_mul_f32 v[64:65], v[64:65], v[180:181] op_sel:[0,1]
	v_pk_mul_f32 v[58:59], v[58:59], v[180:181] op_sel:[0,1]
	v_pk_mul_f32 v[60:61], v[60:61], v[180:181] op_sel:[0,1]
	v_pk_mul_f32 v[54:55], v[54:55], v[180:181] op_sel:[0,1]
	v_pk_mul_f32 v[56:57], v[56:57], v[180:181] op_sel:[0,1]
	v_pk_mul_f32 v[50:51], v[50:51], v[180:181] op_sel:[0,1]
	v_pk_mul_f32 v[52:53], v[52:53], v[180:181] op_sel:[0,1]
	s_waitcnt vmcnt(3)
	v_pk_fma_f32 v[64:65], v[136:137], v[64:65], v[166:167]
	v_pk_fma_f32 v[62:63], v[134:135], v[62:63], v[164:165]
	s_waitcnt vmcnt(2)
	v_pk_fma_f32 v[60:61], v[132:133], v[60:61], v[174:175]
	v_pk_fma_f32 v[58:59], v[130:131], v[58:59], v[172:173]
	s_waitcnt vmcnt(1)
	v_pk_fma_f32 v[56:57], v[144:145], v[56:57], v[178:179]
	v_pk_fma_f32 v[54:55], v[142:143], v[54:55], v[176:177]
	s_waitcnt vmcnt(0)
	v_pk_fma_f32 v[52:53], v[140:141], v[52:53], v[190:191]
	v_pk_fma_f32 v[50:51], v[138:139], v[50:51], v[188:189]
	v_add_u32_e32 v164, 0xa0, v150
	global_load_dwordx4 v[172:175], v[192:193], off nt
	global_load_dwordx4 v[176:179], v[192:193], off offset:64 nt
	global_load_dwordx4 v[188:191], v[192:193], off offset:512 nt
	s_nop 0
	global_load_dwordx4 v[192:195], v[192:193], off offset:576 nt
	ds_read_b64 v[166:167], v184 offset:9344
	v_ashrrev_i32_e32 v165, 31, v164
	v_lshlrev_b64 v[180:181], 12, v[164:165]
	v_lshl_add_u64 v[180:181], s[0:1], 0, v[180:181]
	v_lshl_add_u64 v[180:181], v[180:181], 0, v[168:169]
	s_waitcnt lgkmcnt(0)
	v_pk_mul_f32 v[46:47], v[46:47], v[166:167] op_sel:[0,1]
	v_pk_mul_f32 v[48:49], v[48:49], v[166:167] op_sel:[0,1]
	v_pk_mul_f32 v[42:43], v[42:43], v[166:167] op_sel:[0,1]
	v_pk_mul_f32 v[44:45], v[44:45], v[166:167] op_sel:[0,1]
	v_pk_mul_f32 v[38:39], v[38:39], v[166:167] op_sel:[0,1]
	v_pk_mul_f32 v[40:41], v[40:41], v[166:167] op_sel:[0,1]
	v_pk_mul_f32 v[34:35], v[34:35], v[166:167] op_sel:[0,1]
	v_pk_mul_f32 v[36:37], v[36:37], v[166:167] op_sel:[0,1]
	v_add_u32_e32 v166, 0xb0, v150
	v_ashrrev_i32_e32 v167, 31, v166
	s_waitcnt vmcnt(3)
	v_pk_fma_f32 v[48:49], v[136:137], v[48:49], v[174:175]
	v_pk_fma_f32 v[46:47], v[134:135], v[46:47], v[172:173]
	s_waitcnt vmcnt(2)
	v_pk_fma_f32 v[44:45], v[132:133], v[44:45], v[178:179]
	v_pk_fma_f32 v[42:43], v[130:131], v[42:43], v[176:177]
	s_waitcnt vmcnt(1)
	v_pk_fma_f32 v[40:41], v[144:145], v[40:41], v[190:191]
	v_pk_fma_f32 v[38:39], v[142:143], v[38:39], v[188:189]
	s_waitcnt vmcnt(0)
	v_pk_fma_f32 v[36:37], v[140:141], v[36:37], v[194:195]
	v_pk_fma_f32 v[34:35], v[138:139], v[34:35], v[192:193]
	s_nop 0
	global_load_dwordx4 v[172:175], v[180:181], off nt
	global_load_dwordx4 v[176:179], v[180:181], off offset:64 nt
	global_load_dwordx4 v[188:191], v[180:181], off offset:512 nt
	global_load_dwordx4 v[192:195], v[180:181], off offset:576 nt
	ds_read_b64 v[210:211], v184 offset:9472
	v_lshlrev_b64 v[180:181], 12, v[166:167]
	v_lshl_add_u64 v[180:181], s[0:1], 0, v[180:181]
	v_lshl_add_u64 v[168:169], v[180:181], 0, v[168:169]
	v_mov_b32_e32 v180, v119
	s_waitcnt lgkmcnt(0)
	v_pk_mul_f32 v[30:31], v[30:31], v[210:211] op_sel:[0,1]
	v_pk_mul_f32 v[32:33], v[32:33], v[210:211] op_sel:[0,1]
	v_pk_mul_f32 v[26:27], v[26:27], v[210:211] op_sel:[0,1]
	v_pk_mul_f32 v[28:29], v[28:29], v[210:211] op_sel:[0,1]
	v_pk_mul_f32 v[22:23], v[22:23], v[210:211] op_sel:[0,1]
	v_pk_mul_f32 v[24:25], v[24:25], v[210:211] op_sel:[0,1]
	v_pk_mul_f32 v[18:19], v[18:19], v[210:211] op_sel:[0,1]
	v_pk_mul_f32 v[20:21], v[20:21], v[210:211] op_sel:[0,1]
	v_mov_b32_e32 v181, v120
	s_waitcnt vmcnt(3)
	v_pk_fma_f32 v[32:33], v[136:137], v[32:33], v[174:175]
	v_pk_fma_f32 v[30:31], v[134:135], v[30:31], v[172:173]
	s_waitcnt vmcnt(2)
	v_pk_fma_f32 v[28:29], v[132:133], v[28:29], v[178:179]
	v_pk_fma_f32 v[26:27], v[130:131], v[26:27], v[176:177]
	s_waitcnt vmcnt(1)
	v_pk_fma_f32 v[24:25], v[144:145], v[24:25], v[190:191]
	v_pk_fma_f32 v[22:23], v[142:143], v[22:23], v[188:189]
	s_waitcnt vmcnt(0)
	v_pk_fma_f32 v[20:21], v[140:141], v[20:21], v[194:195]
	v_pk_fma_f32 v[18:19], v[138:139], v[18:19], v[192:193]
	v_pk_add_f32 v[172:173], v[180:181], v[196:197]
	global_load_dwordx4 v[174:177], v[168:169], off nt
	global_load_dwordx4 v[178:181], v[168:169], off offset:64 nt
	global_load_dwordx4 v[188:191], v[168:169], off offset:512 nt
	global_load_dwordx4 v[192:195], v[168:169], off offset:576 nt
	v_add_f32_e32 v196, v204, v206
	v_add_f32_e32 v197, v205, v207
	v_add_f32_e32 v172, v172, v173
	v_add_f32_e32 v168, v196, v196
	v_add_f32_e32 v169, v196, v197
	v_add_f32_e32 v215, 0, v172
	v_add_f32_e32 v204, v208, v212
	v_add_f32_e32 v205, v209, v213
	v_add_f32_e32 v168, v116, v214
	v_add_f32_e32 v169, v169, v215
	s_nop 0
	v_add_f32_e32 v168, v204, v168
	v_add_f32_e32 v169, v205, v169
	s_nop 0
	v_add_f32_e32 v168, v168, v169
	v_mov_b32_e32 v169, v168
	s_nop 1
	v_permlane16_swap_b32_e32 v168, v169
	s_waitcnt lgkmcnt(0)
	v_add_f32_e32 v168, v168, v169
	v_mov_b32_e32 v169, v168
	s_nop 1
	v_permlane32_swap_b32_e32 v168, v169
	s_waitcnt lgkmcnt(0)
	v_add_f32_e32 v168, v168, v169
	v_fmamk_f32 v172, v168, 0xbc800000, v121
	v_fmamk_f32 v187, v168, 0xbc800000, v119
	v_fmamk_f32 v197, v168, 0xbc800000, v125
	v_fmamk_f32 v205, v168, 0xbc800000, v123
	v_fmamk_f32 v169, v168, 0xbc800000, v120
	v_fmamk_f32 v173, v168, 0xbc800000, v118
	v_fmamk_f32 v196, v168, 0xbc800000, v124
	v_fmamk_f32 v204, v168, 0xbc800000, v122
	v_fmamk_f32 v207, v168, 0xbc800000, v129
	v_fmamk_f32 v209, v168, 0xbc800000, v127
	v_mul_f32_e32 v187, v187, v187
	v_mul_f32_e32 v172, v172, v172
	v_mul_f32_e32 v205, v205, v205
	v_mul_f32_e32 v197, v197, v197
	v_fmamk_f32 v206, v168, 0xbc800000, v128
	v_fmamk_f32 v208, v168, 0xbc800000, v126
	v_fmamk_f32 v211, v168, 0xbc800000, v117
	v_fmamk_f32 v213, v168, 0xbc800000, v115
	v_mul_f32_e32 v209, v209, v209
	v_mul_f32_e32 v207, v207, v207
	v_fmac_f32_e32 v187, v173, v173
	v_fmac_f32_e32 v172, v169, v169
	v_fmac_f32_e32 v205, v204, v204
	v_fmac_f32_e32 v197, v196, v196
	v_fmamk_f32 v210, v168, 0xbc800000, v116
	v_fmamk_f32 v212, v168, 0xbc800000, v114
	v_mul_f32_e32 v213, v213, v213
	v_mul_f32_e32 v211, v211, v211
	v_fmac_f32_e32 v209, v208, v208
	v_fmac_f32_e32 v207, v206, v206
	v_add_f32_e32 v169, v187, v172
	v_add_f32_e32 v172, v205, v197
	v_fmac_f32_e32 v213, v212, v212
	v_fmac_f32_e32 v211, v210, v210
	v_add_f32_e32 v173, v209, v207
	v_add_f32_e32 v169, v169, v172
	v_add_f32_e32 v187, v213, v211
	v_add_f32_e32 v169, v173, v169
	v_add_f32_e32 v169, v187, v169
	v_mov_b32_e32 v172, v169
	s_nop 1
	v_permlane16_swap_b32_e32 v169, v172
	ds_read_b64 v[196:197], v184 offset:9600
	s_waitcnt lgkmcnt(1)
	v_add_f32_e32 v169, v169, v172
	ds_bpermute_b32 v172, v202, v169
	s_waitcnt lgkmcnt(1)
	v_mul_f32_e32 v14, v14, v197
	v_mul_f32_e32 v15, v15, v197
	v_mul_f32_e32 v16, v16, v197
	v_mul_f32_e32 v17, v17, v197
	v_mul_f32_e32 v10, v10, v197
	v_mul_f32_e32 v11, v11, v197
	v_mul_f32_e32 v12, v12, v197
	v_mul_f32_e32 v13, v13, v197
	v_mul_f32_e32 v6, v6, v197
	v_mul_f32_e32 v7, v7, v197
	v_mul_f32_e32 v8, v8, v197
	v_mul_f32_e32 v9, v9, v197
	v_mul_f32_e32 v2, v2, v197
	v_mul_f32_e32 v3, v3, v197
	v_mul_f32_e32 v4, v4, v197
	v_mul_f32_e32 v5, v5, v197
	s_waitcnt vmcnt(3)
	v_pk_fma_f32 v[16:17], v[136:137], v[16:17], v[176:177]
	v_pk_fma_f32 v[14:15], v[134:135], v[14:15], v[174:175]
	s_waitcnt vmcnt(2)
	v_pk_fma_f32 v[12:13], v[132:133], v[12:13], v[180:181]
	v_pk_fma_f32 v[10:11], v[130:131], v[10:11], v[178:179]
	s_waitcnt vmcnt(1)
	v_pk_fma_f32 v[8:9], v[144:145], v[8:9], v[190:191]
	v_pk_fma_f32 v[6:7], v[142:143], v[6:7], v[188:189]
	s_waitcnt vmcnt(0)
	v_pk_fma_f32 v[4:5], v[140:141], v[4:5], v[194:195]
	v_pk_fma_f32 v[2:3], v[138:139], v[2:3], v[192:193]
	s_nop 0
	s_and_saveexec_b64 s[0:1], s[4:5]
	s_cbranch_execz .LBB0_612
	s_lshl_b32 s17, s26, 11
	s_add_i32 s17, s27, s17
	v_mul_f32_e32 v130, 0x3c800000, v168
	s_waitcnt lgkmcnt(0)
	v_add_f32_e32 v131, v169, v172
	v_lshl_add_u32 v132, v170, 5, s17
	ds_write_b64 v132, v[130:131]

.LBB0_896:
	s_or_b64 exec, exec, s[20:21]
	s_lshl_b32 s0, s30, 5
	s_lshl_b32 s1, s16, 8
	s_or_b32 s0, s1, s0
	v_lshrrev_b32_e32 v130, 2, v148
	v_and_or_b32 v162, v130, 12, s0
	v_add_u32_e32 v150, s17, v152
	s_lshl_b32 s0, s26, 5
	v_ashrrev_i32_e32 v151, 31, v150
	s_and_b32 s0, s0, 0xfffffc00
	v_ashrrev_i32_e32 v163, 31, v162
	v_lshlrev_b64 v[130:131], 11, v[150:151]
	v_add_u32_e32 v132, s0, v162
	v_lshl_add_u64 v[130:131], s[56:57], 0, v[130:131]
	v_lshlrev_b64 v[168:169], 1, v[162:163]
	s_waitcnt lgkmcnt(0)
	v_ashrrev_i32_e32 v133, 31, v132
	s_waitcnt lgkmcnt(0)
	s_barrier
	v_lshl_add_u64 v[130:131], v[130:131], 0, v[168:169]
	v_lshl_add_u64 v[148:149], v[132:133], 2, s[34:35]
	s_mov_b32 s17, 0x106000
	v_add_co_u32_e32 v130, vcc, s17, v148
	s_mov_b64 s[0:1], 0x106000
	s_nop 0
	v_addc_co_u32_e32 v131, vcc, 0, v149, vcc
	global_load_dwordx4 v[138:141], v[130:131], off
	v_lshl_add_u64 v[130:131], v[148:149], 0, s[0:1]
	global_load_dwordx4 v[142:145], v[130:131], off offset:64
	global_load_dwordx4 v[134:137], v[130:131], off offset:512
	s_nop 0
	global_load_dwordx4 v[130:133], v[130:131], off offset:576
	v_lshl_add_u32 v246, v150, 11, v168
	global_load_dwordx2 v[216:217], v246, s[56:57] nt
	global_load_dwordx2 v[218:219], v246, s[56:57] offset:32 nt
	global_load_dwordx2 v[220:221], v246, s[56:57] offset:256 nt
	global_load_dwordx2 v[222:223], v246, s[56:57] offset:288 nt
	v_add_u32_e32 v247, 0x8000, v246
	global_load_dwordx2 v[224:225], v247, s[56:57] nt
	global_load_dwordx2 v[232:233], v247, s[56:57] offset:32 nt
	global_load_dwordx2 v[234:235], v247, s[56:57] offset:256 nt
	global_load_dwordx2 v[236:237], v247, s[56:57] offset:288 nt
	v_add_u32_e32 v247, 0x10000, v246
	global_load_dwordx2 v[238:239], v247, s[56:57] nt
	global_load_dwordx2 v[240:241], v247, s[56:57] offset:32 nt
	global_load_dwordx2 v[242:243], v247, s[56:57] offset:256 nt
	global_load_dwordx2 v[244:245], v247, s[56:57] offset:288 nt
	v_lshl_add_u32 v185, v152, 3, 0
	ds_read_b64 v[164:165], v185 offset:8192
	v_add_u32_e32 v152, 16, v150
	v_ashrrev_i32_e32 v153, 31, v152
	v_lshlrev_b64 v[166:167], 11, v[152:153]
	v_lshl_add_u64 v[166:167], s[56:57], 0, v[166:167]
	s_waitcnt lgkmcnt(0)
	v_pk_mul_f32 v[128:129], v[128:129], v[164:165] op_sel:[0,1]
	v_pk_mul_f32 v[126:127], v[126:127], v[164:165] op_sel:[0,1]
	v_pk_mul_f32 v[122:123], v[122:123], v[164:165] op_sel:[0,1]
	v_pk_mul_f32 v[124:125], v[124:125], v[164:165] op_sel:[0,1]
	v_pk_mul_f32 v[172:173], v[118:119], v[164:165] op_sel:[0,1]
	v_pk_mul_f32 v[174:175], v[120:121], v[164:165] op_sel:[0,1]
	v_pk_mul_f32 v[114:115], v[114:115], v[164:165] op_sel:[0,1]
	v_pk_mul_f32 v[116:117], v[116:117], v[164:165] op_sel:[0,1]
	v_lshl_add_u64 v[166:167], v[166:167], 0, v[168:169]
	s_waitcnt vmcnt(11)
	v_lshlrev_b32_e32 v118, 16, v216
	v_and_b32_e32 v119, 0xffff0000, v216
	v_lshlrev_b32_e32 v120, 16, v217
	v_and_b32_e32 v121, 0xffff0000, v217
	s_waitcnt vmcnt(10)
	v_lshlrev_b32_e32 v154, 16, v218
	v_and_b32_e32 v155, 0xffff0000, v218
	v_lshlrev_b32_e32 v156, 16, v219
	v_and_b32_e32 v157, 0xffff0000, v219
	s_waitcnt vmcnt(9)
	v_lshlrev_b32_e32 v164, 16, v220
	v_and_b32_e32 v165, 0xffff0000, v220
	v_lshlrev_b32_e32 v158, 16, v221
	v_and_b32_e32 v159, 0xffff0000, v221
	s_waitcnt vmcnt(8)
	v_lshlrev_b32_e32 v176, 16, v222
	v_and_b32_e32 v177, 0xffff0000, v222
	v_lshlrev_b32_e32 v160, 16, v223
	v_and_b32_e32 v161, 0xffff0000, v223
	v_pk_fma_f32 v[118:119], v[138:139], v[126:127], v[118:119]
	v_pk_fma_f32 v[120:121], v[140:141], v[128:129], v[120:121]
	v_pk_fma_f32 v[124:125], v[144:145], v[124:125], v[156:157]
	v_pk_fma_f32 v[122:123], v[142:143], v[122:123], v[154:155]
	v_pk_fma_f32 v[128:129], v[136:137], v[174:175], v[158:159]
	v_pk_fma_f32 v[126:127], v[134:135], v[172:173], v[164:165]
	v_pk_fma_f32 v[116:117], v[132:133], v[116:117], v[160:161]
	v_pk_fma_f32 v[114:115], v[130:131], v[114:115], v[176:177]
	v_add_u32_e32 v154, 32, v150
	v_add_u32_e32 v247, 0x18000, v246
	global_load_dwordx2 v[216:217], v247, s[56:57] nt
	global_load_dwordx2 v[218:219], v247, s[56:57] offset:32 nt
	global_load_dwordx2 v[220:221], v247, s[56:57] offset:256 nt
	global_load_dwordx2 v[222:223], v247, s[56:57] offset:288 nt
	ds_read_b64 v[166:167], v185 offset:8320
	v_ashrrev_i32_e32 v155, 31, v154
	v_lshlrev_b64 v[172:173], 11, v[154:155]
	v_lshl_add_u64 v[172:173], s[56:57], 0, v[172:173]
	v_lshl_add_u64 v[172:173], v[172:173], 0, v[168:169]
	s_waitcnt lgkmcnt(0)
	v_pk_mul_f32 v[110:111], v[110:111], v[166:167] op_sel:[0,1]
	v_pk_mul_f32 v[112:113], v[112:113], v[166:167] op_sel:[0,1]
	v_pk_mul_f32 v[106:107], v[106:107], v[166:167] op_sel:[0,1]
	v_pk_mul_f32 v[108:109], v[108:109], v[166:167] op_sel:[0,1]
	v_pk_mul_f32 v[102:103], v[102:103], v[166:167] op_sel:[0,1]
	v_pk_mul_f32 v[104:105], v[104:105], v[166:167] op_sel:[0,1]
	v_pk_mul_f32 v[98:99], v[98:99], v[166:167] op_sel:[0,1]
	v_pk_mul_f32 v[100:101], v[100:101], v[166:167] op_sel:[0,1]
	v_add_f32_e32 v195, v126, v127
	v_add_f32_e32 v205, v128, v129
	v_mov_b32_e32 v194, v114
	v_mov_b32_e32 v204, v115
	v_mov_b32_e32 v206, v117
	s_waitcnt vmcnt(11)
	v_lshlrev_b32_e32 v166, 16, v224
	v_and_b32_e32 v167, 0xffff0000, v224
	v_lshlrev_b32_e32 v156, 16, v225
	v_and_b32_e32 v157, 0xffff0000, v225
	s_waitcnt vmcnt(10)
	v_lshlrev_b32_e32 v174, 16, v232
	v_and_b32_e32 v175, 0xffff0000, v232
	v_lshlrev_b32_e32 v158, 16, v233
	v_and_b32_e32 v159, 0xffff0000, v233
	s_waitcnt vmcnt(9)
	v_lshlrev_b32_e32 v176, 16, v234
	v_and_b32_e32 v177, 0xffff0000, v234
	v_lshlrev_b32_e32 v160, 16, v235
	v_and_b32_e32 v161, 0xffff0000, v235
	s_waitcnt vmcnt(8)
	v_lshlrev_b32_e32 v178, 16, v236
	v_and_b32_e32 v179, 0xffff0000, v236
	v_lshlrev_b32_e32 v164, 16, v237
	v_and_b32_e32 v165, 0xffff0000, v237
	v_pk_fma_f32 v[112:113], v[140:141], v[112:113], v[156:157]
	v_pk_fma_f32 v[110:111], v[138:139], v[110:111], v[166:167]
	v_pk_fma_f32 v[108:109], v[144:145], v[108:109], v[158:159]
	v_pk_fma_f32 v[106:107], v[142:143], v[106:107], v[174:175]
	v_pk_fma_f32 v[104:105], v[136:137], v[104:105], v[160:161]
	v_pk_fma_f32 v[102:103], v[134:135], v[102:103], v[176:177]
	v_pk_fma_f32 v[100:101], v[132:133], v[100:101], v[164:165]
	v_pk_fma_f32 v[98:99], v[130:131], v[98:99], v[178:179]
	v_add_u32_e32 v156, 48, v150
	v_add_u32_e32 v247, 0x40000, v246
	global_load_dwordx2 v[224:225], v247, s[56:57] nt
	global_load_dwordx2 v[232:233], v247, s[56:57] offset:32 nt
	global_load_dwordx2 v[234:235], v247, s[56:57] offset:256 nt
	global_load_dwordx2 v[236:237], v247, s[56:57] offset:288 nt
	ds_read_b64 v[172:173], v185 offset:8448
	v_ashrrev_i32_e32 v157, 31, v156
	v_lshlrev_b64 v[174:175], 11, v[156:157]
	v_lshl_add_u64 v[174:175], s[56:57], 0, v[174:175]
	v_lshl_add_u64 v[174:175], v[174:175], 0, v[168:169]
	s_waitcnt lgkmcnt(0)
	v_pk_mul_f32 v[94:95], v[94:95], v[172:173] op_sel:[0,1]
	v_pk_mul_f32 v[96:97], v[96:97], v[172:173] op_sel:[0,1]
	v_pk_mul_f32 v[90:91], v[90:91], v[172:173] op_sel:[0,1]
	v_pk_mul_f32 v[92:93], v[92:93], v[172:173] op_sel:[0,1]
	v_pk_mul_f32 v[86:87], v[86:87], v[172:173] op_sel:[0,1]
	v_pk_mul_f32 v[88:89], v[88:89], v[172:173] op_sel:[0,1]
	v_pk_mul_f32 v[82:83], v[82:83], v[172:173] op_sel:[0,1]
	v_pk_mul_f32 v[84:85], v[84:85], v[172:173] op_sel:[0,1]
	s_waitcnt vmcnt(11)
	v_lshlrev_b32_e32 v172, 16, v238
	v_and_b32_e32 v173, 0xffff0000, v238
	v_lshlrev_b32_e32 v158, 16, v239
	v_and_b32_e32 v159, 0xffff0000, v239
	s_waitcnt vmcnt(10)
	v_lshlrev_b32_e32 v176, 16, v240
	v_and_b32_e32 v177, 0xffff0000, v240
	v_lshlrev_b32_e32 v160, 16, v241
	v_and_b32_e32 v161, 0xffff0000, v241
	s_waitcnt vmcnt(9)
	v_lshlrev_b32_e32 v178, 16, v242
	v_and_b32_e32 v179, 0xffff0000, v242
	v_lshlrev_b32_e32 v164, 16, v243
	v_and_b32_e32 v165, 0xffff0000, v243
	s_waitcnt vmcnt(8)
	v_lshlrev_b32_e32 v180, 16, v244
	v_and_b32_e32 v181, 0xffff0000, v244
	v_lshlrev_b32_e32 v166, 16, v245
	v_and_b32_e32 v167, 0xffff0000, v245
	v_pk_fma_f32 v[96:97], v[140:141], v[96:97], v[158:159]
	v_pk_fma_f32 v[94:95], v[138:139], v[94:95], v[172:173]
	v_pk_fma_f32 v[92:93], v[144:145], v[92:93], v[160:161]
	v_pk_fma_f32 v[90:91], v[142:143], v[90:91], v[176:177]
	v_pk_fma_f32 v[88:89], v[136:137], v[88:89], v[164:165]
	v_pk_fma_f32 v[86:87], v[134:135], v[86:87], v[178:179]
	v_pk_fma_f32 v[84:85], v[132:133], v[84:85], v[166:167]
	v_pk_fma_f32 v[82:83], v[130:131], v[82:83], v[180:181]
	v_add_u32_e32 v158, 0x80, v150
	v_add_u32_e32 v247, 0x48000, v246
	global_load_dwordx2 v[238:239], v247, s[56:57] nt
	global_load_dwordx2 v[240:241], v247, s[56:57] offset:32 nt
	global_load_dwordx2 v[242:243], v247, s[56:57] offset:256 nt
	global_load_dwordx2 v[244:245], v247, s[56:57] offset:288 nt
	ds_read_b64 v[174:175], v185 offset:8576
	v_ashrrev_i32_e32 v159, 31, v158
	v_lshlrev_b64 v[176:177], 11, v[158:159]
	v_lshl_add_u64 v[176:177], s[56:57], 0, v[176:177]
	v_lshl_add_u64 v[176:177], v[176:177], 0, v[168:169]
	s_waitcnt lgkmcnt(0)
	v_pk_mul_f32 v[78:79], v[78:79], v[174:175] op_sel:[0,1]
	v_pk_mul_f32 v[80:81], v[80:81], v[174:175] op_sel:[0,1]
	v_pk_mul_f32 v[74:75], v[74:75], v[174:175] op_sel:[0,1]
	v_pk_mul_f32 v[76:77], v[76:77], v[174:175] op_sel:[0,1]
	v_pk_mul_f32 v[70:71], v[70:71], v[174:175] op_sel:[0,1]
	v_pk_mul_f32 v[72:73], v[72:73], v[174:175] op_sel:[0,1]
	v_pk_mul_f32 v[66:67], v[66:67], v[174:175] op_sel:[0,1]
	v_pk_mul_f32 v[68:69], v[68:69], v[174:175] op_sel:[0,1]
	s_waitcnt vmcnt(11)
	v_lshlrev_b32_e32 v174, 16, v216
	v_and_b32_e32 v175, 0xffff0000, v216
	v_lshlrev_b32_e32 v160, 16, v217
	v_and_b32_e32 v161, 0xffff0000, v217
	s_waitcnt vmcnt(10)
	v_lshlrev_b32_e32 v178, 16, v218
	v_and_b32_e32 v179, 0xffff0000, v218
	v_lshlrev_b32_e32 v164, 16, v219
	v_and_b32_e32 v165, 0xffff0000, v219
	s_waitcnt vmcnt(9)
	v_lshlrev_b32_e32 v180, 16, v220
	v_and_b32_e32 v181, 0xffff0000, v220
	v_lshlrev_b32_e32 v166, 16, v221
	v_and_b32_e32 v167, 0xffff0000, v221
	s_waitcnt vmcnt(8)
	v_lshlrev_b32_e32 v188, 16, v222
	v_and_b32_e32 v189, 0xffff0000, v222
	v_lshlrev_b32_e32 v172, 16, v223
	v_and_b32_e32 v173, 0xffff0000, v223
	v_pk_fma_f32 v[80:81], v[140:141], v[80:81], v[160:161]
	v_pk_fma_f32 v[78:79], v[138:139], v[78:79], v[174:175]
	v_pk_fma_f32 v[76:77], v[144:145], v[76:77], v[164:165]
	v_pk_fma_f32 v[74:75], v[142:143], v[74:75], v[178:179]
	v_pk_fma_f32 v[72:73], v[136:137], v[72:73], v[166:167]
	v_pk_fma_f32 v[70:71], v[134:135], v[70:71], v[180:181]
	v_pk_fma_f32 v[68:69], v[132:133], v[68:69], v[172:173]
	v_pk_fma_f32 v[66:67], v[130:131], v[66:67], v[188:189]
	v_add_u32_e32 v160, 0x90, v150
	v_add_u32_e32 v247, 0x50000, v246
	global_load_dwordx2 v[216:217], v247, s[56:57] nt
	global_load_dwordx2 v[218:219], v247, s[56:57] offset:32 nt
	global_load_dwordx2 v[220:221], v247, s[56:57] offset:256 nt
	global_load_dwordx2 v[222:223], v247, s[56:57] offset:288 nt
	ds_read_b64 v[176:177], v185 offset:9216
	v_ashrrev_i32_e32 v161, 31, v160
	v_lshlrev_b64 v[178:179], 11, v[160:161]
	v_lshl_add_u64 v[178:179], s[56:57], 0, v[178:179]
	v_lshl_add_u64 v[178:179], v[178:179], 0, v[168:169]
	s_waitcnt lgkmcnt(0)
	v_pk_mul_f32 v[62:63], v[62:63], v[176:177] op_sel:[0,1]
	v_pk_mul_f32 v[64:65], v[64:65], v[176:177] op_sel:[0,1]
	v_pk_mul_f32 v[58:59], v[58:59], v[176:177] op_sel:[0,1]
	v_pk_mul_f32 v[60:61], v[60:61], v[176:177] op_sel:[0,1]
	v_pk_mul_f32 v[54:55], v[54:55], v[176:177] op_sel:[0,1]
	v_pk_mul_f32 v[56:57], v[56:57], v[176:177] op_sel:[0,1]
	v_pk_mul_f32 v[50:51], v[50:51], v[176:177] op_sel:[0,1]
	v_pk_mul_f32 v[52:53], v[52:53], v[176:177] op_sel:[0,1]
	s_waitcnt vmcnt(11)
	v_lshlrev_b32_e32 v176, 16, v224
	v_and_b32_e32 v177, 0xffff0000, v224
	v_lshlrev_b32_e32 v164, 16, v225
	v_and_b32_e32 v165, 0xffff0000, v225
	s_waitcnt vmcnt(10)
	v_lshlrev_b32_e32 v180, 16, v232
	v_and_b32_e32 v181, 0xffff0000, v232
	v_lshlrev_b32_e32 v166, 16, v233
	v_and_b32_e32 v167, 0xffff0000, v233
	s_waitcnt vmcnt(9)
	v_lshlrev_b32_e32 v188, 16, v234
	v_and_b32_e32 v189, 0xffff0000, v234
	v_lshlrev_b32_e32 v172, 16, v235
	v_and_b32_e32 v173, 0xffff0000, v235
	s_waitcnt vmcnt(8)
	v_lshlrev_b32_e32 v190, 16, v236
	v_and_b32_e32 v191, 0xffff0000, v236
	v_lshlrev_b32_e32 v174, 16, v237
	v_and_b32_e32 v175, 0xffff0000, v237
	v_pk_fma_f32 v[64:65], v[140:141], v[64:65], v[164:165]
	v_pk_fma_f32 v[62:63], v[138:139], v[62:63], v[176:177]
	v_pk_fma_f32 v[60:61], v[144:145], v[60:61], v[166:167]
	v_pk_fma_f32 v[58:59], v[142:143], v[58:59], v[180:181]
	v_pk_fma_f32 v[56:57], v[136:137], v[56:57], v[172:173]
	v_pk_fma_f32 v[54:55], v[134:135], v[54:55], v[188:189]
	v_pk_fma_f32 v[52:53], v[132:133], v[52:53], v[174:175]
	v_pk_fma_f32 v[50:51], v[130:131], v[50:51], v[190:191]
	v_add_u32_e32 v164, 0xa0, v150
	v_add_u32_e32 v247, 0x58000, v246
	global_load_dwordx2 v[224:225], v247, s[56:57] nt
	global_load_dwordx2 v[232:233], v247, s[56:57] offset:32 nt
	global_load_dwordx2 v[234:235], v247, s[56:57] offset:256 nt
	global_load_dwordx2 v[236:237], v247, s[56:57] offset:288 nt
	ds_read_b64 v[178:179], v185 offset:9344
	v_ashrrev_i32_e32 v165, 31, v164
	v_lshlrev_b64 v[180:181], 11, v[164:165]
	v_lshl_add_u64 v[180:181], s[56:57], 0, v[180:181]
	v_lshl_add_u64 v[180:181], v[180:181], 0, v[168:169]
	s_waitcnt lgkmcnt(0)
	v_pk_mul_f32 v[46:47], v[46:47], v[178:179] op_sel:[0,1]
	v_pk_mul_f32 v[48:49], v[48:49], v[178:179] op_sel:[0,1]
	v_pk_mul_f32 v[42:43], v[42:43], v[178:179] op_sel:[0,1]
	v_pk_mul_f32 v[44:45], v[44:45], v[178:179] op_sel:[0,1]
	v_pk_mul_f32 v[38:39], v[38:39], v[178:179] op_sel:[0,1]
	v_pk_mul_f32 v[40:41], v[40:41], v[178:179] op_sel:[0,1]
	v_pk_mul_f32 v[34:35], v[34:35], v[178:179] op_sel:[0,1]
	v_pk_mul_f32 v[36:37], v[36:37], v[178:179] op_sel:[0,1]
	s_waitcnt vmcnt(11)
	v_lshlrev_b32_e32 v178, 16, v238
	v_and_b32_e32 v179, 0xffff0000, v238
	v_lshlrev_b32_e32 v166, 16, v239
	v_and_b32_e32 v167, 0xffff0000, v239
	s_waitcnt vmcnt(10)
	v_lshlrev_b32_e32 v188, 16, v240
	v_and_b32_e32 v189, 0xffff0000, v240
	v_lshlrev_b32_e32 v172, 16, v241
	v_and_b32_e32 v173, 0xffff0000, v241
	s_waitcnt vmcnt(9)
	v_lshlrev_b32_e32 v190, 16, v242
	v_and_b32_e32 v191, 0xffff0000, v242
	v_lshlrev_b32_e32 v174, 16, v243
	v_and_b32_e32 v175, 0xffff0000, v243
	s_waitcnt vmcnt(8)
	v_lshlrev_b32_e32 v192, 16, v244
	v_and_b32_e32 v193, 0xffff0000, v244
	v_lshlrev_b32_e32 v176, 16, v245
	v_and_b32_e32 v177, 0xffff0000, v245
	v_pk_fma_f32 v[48:49], v[140:141], v[48:49], v[166:167]
	v_pk_fma_f32 v[46:47], v[138:139], v[46:47], v[178:179]
	v_pk_fma_f32 v[44:45], v[144:145], v[44:45], v[172:173]
	v_pk_fma_f32 v[42:43], v[142:143], v[42:43], v[188:189]
	v_pk_fma_f32 v[40:41], v[136:137], v[40:41], v[174:175]
	v_pk_fma_f32 v[38:39], v[134:135], v[38:39], v[190:191]
	v_pk_fma_f32 v[36:37], v[132:133], v[36:37], v[176:177]
	v_pk_fma_f32 v[34:35], v[130:131], v[34:35], v[192:193]
	v_add_u32_e32 v166, 0xb0, v150
	ds_read_b64 v[196:197], v185 offset:9472
	v_ashrrev_i32_e32 v167, 31, v166
	v_lshlrev_b64 v[180:181], 11, v[166:167]
	v_lshl_add_u64 v[180:181], s[56:57], 0, v[180:181]
	v_lshl_add_u64 v[168:169], v[180:181], 0, v[168:169]
	s_waitcnt lgkmcnt(0)
	v_mul_f32_e32 v30, v30, v197
	v_mul_f32_e32 v31, v31, v197
	v_mul_f32_e32 v32, v32, v197
	v_mul_f32_e32 v33, v33, v197
	v_mul_f32_e32 v26, v26, v197
	v_mul_f32_e32 v27, v27, v197
	v_mul_f32_e32 v28, v28, v197
	v_mul_f32_e32 v29, v29, v197
	v_mul_f32_e32 v22, v22, v197
	v_mul_f32_e32 v23, v23, v197
	v_mul_f32_e32 v24, v24, v197
	v_mul_f32_e32 v25, v25, v197
	v_mul_f32_e32 v18, v18, v197
	v_mul_f32_e32 v19, v19, v197
	v_mul_f32_e32 v20, v20, v197
	v_mul_f32_e32 v21, v21, v197
	s_waitcnt vmcnt(7)
	v_lshlrev_b32_e32 v196, 16, v216
	v_and_b32_e32 v197, 0xffff0000, v216
	v_lshlrev_b32_e32 v172, 16, v217
	v_and_b32_e32 v173, 0xffff0000, v217
	s_waitcnt vmcnt(5)
	v_lshlrev_b32_e32 v210, 16, v220
	v_and_b32_e32 v211, 0xffff0000, v220
	v_lshlrev_b32_e32 v176, 16, v221
	v_and_b32_e32 v177, 0xffff0000, v221
	v_pk_fma_f32 v[32:33], v[140:141], v[32:33], v[172:173]
	v_pk_fma_f32 v[24:25], v[136:137], v[24:25], v[176:177]
	v_add_f32_e32 v172, v119, v118
	v_add_f32_e32 v173, v120, v121
	v_add_f32_e32 v176, v123, v122
	v_add_f32_e32 v177, v124, v125
	v_add_f32_e32 v188, v172, v173
	v_add_f32_e32 v172, v176, v176
	v_add_f32_e32 v173, v176, v177
	s_waitcnt vmcnt(6)
	v_lshlrev_b32_e32 v208, 16, v218
	v_and_b32_e32 v209, 0xffff0000, v218
	v_lshlrev_b32_e32 v174, 16, v219
	v_and_b32_e32 v175, 0xffff0000, v219
	s_waitcnt vmcnt(4)
	v_lshlrev_b32_e32 v212, 16, v222
	v_and_b32_e32 v213, 0xffff0000, v222
	v_lshlrev_b32_e32 v178, 16, v223
	v_and_b32_e32 v179, 0xffff0000, v223
	v_add_f32_e32 v207, 0, v188
	v_pk_fma_f32 v[30:31], v[138:139], v[30:31], v[196:197]
	v_pk_fma_f32 v[28:29], v[144:145], v[28:29], v[174:175]
	v_pk_fma_f32 v[26:27], v[142:143], v[26:27], v[208:209]
	v_pk_fma_f32 v[22:23], v[134:135], v[22:23], v[210:211]
	v_pk_fma_f32 v[20:21], v[132:133], v[20:21], v[178:179]
	v_pk_fma_f32 v[18:19], v[130:131], v[18:19], v[212:213]
	v_add_f32_e32 v178, v194, v204
	v_add_f32_e32 v179, v195, v205
	v_add_f32_e32 v172, v116, v206
	v_add_f32_e32 v173, v173, v207
	v_add_f32_e32 v172, v178, v172
	v_add_f32_e32 v173, v179, v173
	v_add_f32_e32 v168, v172, v173
	v_mov_b32_e32 v169, v168
	s_nop 1
	v_permlane16_swap_b32_e32 v168, v169
	s_waitcnt lgkmcnt(0)
	v_add_f32_e32 v168, v168, v169
	v_mov_b32_e32 v169, v168
	s_nop 1
	v_permlane32_swap_b32_e32 v168, v169
	s_waitcnt lgkmcnt(0)
	v_add_f32_e32 v168, v168, v169
	v_fmamk_f32 v172, v168, 0xbc800000, v121
	v_fmamk_f32 v188, v168, 0xbc800000, v119
	v_fmamk_f32 v190, v168, 0xbc800000, v125
	v_fmamk_f32 v192, v168, 0xbc800000, v123
	v_fmamk_f32 v169, v168, 0xbc800000, v120
	v_fmamk_f32 v173, v168, 0xbc800000, v118
	v_fmamk_f32 v189, v168, 0xbc800000, v124
	v_fmamk_f32 v191, v168, 0xbc800000, v122
	v_fmamk_f32 v194, v168, 0xbc800000, v129
	v_fmamk_f32 v196, v168, 0xbc800000, v127
	v_mul_f32_e32 v188, v188, v188
	v_mul_f32_e32 v172, v172, v172
	v_mul_f32_e32 v192, v192, v192
	v_mul_f32_e32 v190, v190, v190
	v_fmamk_f32 v193, v168, 0xbc800000, v128
	v_fmamk_f32 v195, v168, 0xbc800000, v126
	v_fmamk_f32 v200, v168, 0xbc800000, v117
	v_fmamk_f32 v205, v168, 0xbc800000, v115
	v_mul_f32_e32 v196, v196, v196
	v_mul_f32_e32 v194, v194, v194
	v_fmac_f32_e32 v188, v173, v173
	v_fmac_f32_e32 v172, v169, v169
	v_fmac_f32_e32 v192, v191, v191
	v_fmac_f32_e32 v190, v189, v189
	v_fmamk_f32 v197, v168, 0xbc800000, v116
	v_fmamk_f32 v204, v168, 0xbc800000, v114
	v_mul_f32_e32 v205, v205, v205
	v_mul_f32_e32 v200, v200, v200
	v_fmac_f32_e32 v196, v195, v195
	v_fmac_f32_e32 v194, v193, v193
	v_add_f32_e32 v169, v188, v172
	v_add_f32_e32 v172, v192, v190
	v_fmac_f32_e32 v205, v204, v204
	v_fmac_f32_e32 v200, v197, v197
	v_add_f32_e32 v173, v196, v194
	v_add_f32_e32 v169, v169, v172
	v_add_f32_e32 v188, v205, v200
	v_add_f32_e32 v169, v173, v169
	v_add_f32_e32 v169, v188, v169
	v_mov_b32_e32 v172, v169
	s_nop 1
	v_permlane16_swap_b32_e32 v169, v172
	ds_read_b64 v[188:189], v185 offset:9600
	s_waitcnt lgkmcnt(1)
	v_add_f32_e32 v169, v169, v172
	ds_bpermute_b32 v172, v202, v169
	s_waitcnt lgkmcnt(1)
	v_mul_f32_e32 v14, v14, v189
	v_mul_f32_e32 v15, v15, v189
	v_mul_f32_e32 v16, v16, v189
	v_mul_f32_e32 v17, v17, v189
	v_mul_f32_e32 v10, v10, v189
	v_mul_f32_e32 v11, v11, v189
	v_mul_f32_e32 v12, v12, v189
	v_mul_f32_e32 v13, v13, v189
	v_mul_f32_e32 v6, v6, v189
	v_mul_f32_e32 v7, v7, v189
	v_mul_f32_e32 v8, v8, v189
	v_mul_f32_e32 v9, v9, v189
	v_mul_f32_e32 v2, v2, v189
	v_mul_f32_e32 v3, v3, v189
	v_mul_f32_e32 v4, v4, v189
	v_mul_f32_e32 v5, v5, v189
	s_waitcnt vmcnt(3)
	v_lshlrev_b32_e32 v188, 16, v224
	v_and_b32_e32 v189, 0xffff0000, v224
	v_lshlrev_b32_e32 v174, 16, v225
	v_and_b32_e32 v175, 0xffff0000, v225
	s_waitcnt vmcnt(2)
	v_lshlrev_b32_e32 v190, 16, v232
	v_and_b32_e32 v191, 0xffff0000, v232
	v_lshlrev_b32_e32 v180, 16, v233
	v_and_b32_e32 v181, 0xffff0000, v233
	s_waitcnt vmcnt(1)
	v_lshlrev_b32_e32 v192, 16, v234
	v_and_b32_e32 v193, 0xffff0000, v234
	v_lshlrev_b32_e32 v176, 16, v235
	v_and_b32_e32 v177, 0xffff0000, v235
	s_waitcnt vmcnt(0)
	v_lshlrev_b32_e32 v194, 16, v236
	v_and_b32_e32 v195, 0xffff0000, v236
	v_lshlrev_b32_e32 v178, 16, v237
	v_and_b32_e32 v179, 0xffff0000, v237
	v_pk_fma_f32 v[16:17], v[140:141], v[16:17], v[174:175]
	v_pk_fma_f32 v[14:15], v[138:139], v[14:15], v[188:189]
	v_pk_fma_f32 v[12:13], v[144:145], v[12:13], v[180:181]
	v_pk_fma_f32 v[10:11], v[142:143], v[10:11], v[190:191]
	v_pk_fma_f32 v[8:9], v[136:137], v[8:9], v[176:177]
	v_pk_fma_f32 v[6:7], v[134:135], v[6:7], v[192:193]
	v_pk_fma_f32 v[4:5], v[132:133], v[4:5], v[178:179]
	v_pk_fma_f32 v[2:3], v[130:131], v[2:3], v[194:195]
	s_nop 0
	s_and_saveexec_b64 s[0:1], s[6:7]
	s_cbranch_execz .LBB0_898
	s_lshl_b32 s17, s27, 11
	s_add_i32 s17, s28, s17
	v_mul_f32_e32 v130, 0x3c800000, v168
	s_waitcnt lgkmcnt(0)
	v_add_f32_e32 v131, v169, v172
	v_lshl_add_u32 v132, v170, 5, s17
	ds_write_b64 v132, v[130:131]

.LBB0_1491:
	s_or_b64 exec, exec, s[22:23]
	s_lshl_b32 s0, s40, 5
	s_lshl_b32 s1, s18, 8
	s_or_b32 s0, s1, s0
	v_lshrrev_b32_e32 v130, 2, v148
	v_and_or_b32 v162, v130, 12, s0
	v_add_u32_e32 v150, s19, v152
	s_lshl_b32 s0, s16, 5
	v_ashrrev_i32_e32 v151, 31, v150
	s_and_b32 s0, s0, 0xfffffc00
	v_ashrrev_i32_e32 v163, 31, v162
	v_lshlrev_b64 v[130:131], 11, v[150:151]
	v_add_u32_e32 v132, s0, v162
	v_lshl_add_u64 v[130:131], s[94:95], 0, v[130:131]
	v_lshlrev_b64 v[168:169], 1, v[162:163]
	s_waitcnt lgkmcnt(0)
	v_ashrrev_i32_e32 v133, 31, v132
	s_waitcnt lgkmcnt(0)
	s_barrier
	v_lshl_add_u64 v[130:131], v[130:131], 0, v[168:169]
	v_lshl_add_u64 v[148:149], v[132:133], 2, s[34:35]
	s_mov_b32 s19, 0x10c000
	v_add_co_u32_e32 v130, vcc, s19, v148
	s_mov_b64 s[0:1], 0x10c000
	s_nop 0
	v_addc_co_u32_e32 v131, vcc, 0, v149, vcc
	global_load_dwordx4 v[138:141], v[130:131], off
	v_lshl_add_u64 v[130:131], v[148:149], 0, s[0:1]
	global_load_dwordx4 v[142:145], v[130:131], off offset:64
	global_load_dwordx4 v[134:137], v[130:131], off offset:512
	s_nop 0
	global_load_dwordx4 v[130:133], v[130:131], off offset:576
	v_lshl_add_u32 v246, v150, 11, v168
	global_load_dwordx2 v[216:217], v246, s[94:95] nt
	global_load_dwordx2 v[218:219], v246, s[94:95] offset:32 nt
	global_load_dwordx2 v[220:221], v246, s[94:95] offset:256 nt
	global_load_dwordx2 v[222:223], v246, s[94:95] offset:288 nt
	v_add_u32_e32 v247, 0x8000, v246
	global_load_dwordx2 v[224:225], v247, s[94:95] nt
	global_load_dwordx2 v[232:233], v247, s[94:95] offset:32 nt
	global_load_dwordx2 v[234:235], v247, s[94:95] offset:256 nt
	global_load_dwordx2 v[236:237], v247, s[94:95] offset:288 nt
	v_add_u32_e32 v247, 0x10000, v246
	global_load_dwordx2 v[238:239], v247, s[94:95] nt
	global_load_dwordx2 v[240:241], v247, s[94:95] offset:32 nt
	global_load_dwordx2 v[242:243], v247, s[94:95] offset:256 nt
	global_load_dwordx2 v[244:245], v247, s[94:95] offset:288 nt
	v_lshl_add_u32 v183, v152, 3, 0
	ds_read_b64 v[164:165], v183 offset:8192
	v_add_u32_e32 v152, 16, v150
	v_ashrrev_i32_e32 v153, 31, v152
	v_lshlrev_b64 v[166:167], 11, v[152:153]
	v_lshl_add_u64 v[166:167], s[94:95], 0, v[166:167]
	s_waitcnt lgkmcnt(0)
	v_pk_mul_f32 v[128:129], v[128:129], v[164:165] op_sel:[0,1]
	v_pk_mul_f32 v[126:127], v[126:127], v[164:165] op_sel:[0,1]
	v_pk_mul_f32 v[122:123], v[122:123], v[164:165] op_sel:[0,1]
	v_pk_mul_f32 v[124:125], v[124:125], v[164:165] op_sel:[0,1]
	v_pk_mul_f32 v[172:173], v[118:119], v[164:165] op_sel:[0,1]
	v_pk_mul_f32 v[174:175], v[120:121], v[164:165] op_sel:[0,1]
	v_pk_mul_f32 v[114:115], v[114:115], v[164:165] op_sel:[0,1]
	v_pk_mul_f32 v[116:117], v[116:117], v[164:165] op_sel:[0,1]
	v_lshl_add_u64 v[166:167], v[166:167], 0, v[168:169]
	s_waitcnt vmcnt(11)
	v_lshlrev_b32_e32 v118, 16, v216
	v_and_b32_e32 v119, 0xffff0000, v216
	v_lshlrev_b32_e32 v120, 16, v217
	v_and_b32_e32 v121, 0xffff0000, v217
	s_waitcnt vmcnt(10)
	v_lshlrev_b32_e32 v154, 16, v218
	v_and_b32_e32 v155, 0xffff0000, v218
	v_lshlrev_b32_e32 v156, 16, v219
	v_and_b32_e32 v157, 0xffff0000, v219
	s_waitcnt vmcnt(9)
	v_lshlrev_b32_e32 v164, 16, v220
	v_and_b32_e32 v165, 0xffff0000, v220
	v_lshlrev_b32_e32 v158, 16, v221
	v_and_b32_e32 v159, 0xffff0000, v221
	s_waitcnt vmcnt(8)
	v_lshlrev_b32_e32 v176, 16, v222
	v_and_b32_e32 v177, 0xffff0000, v222
	v_lshlrev_b32_e32 v160, 16, v223
	v_and_b32_e32 v161, 0xffff0000, v223
	v_pk_fma_f32 v[118:119], v[138:139], v[126:127], v[118:119]
	v_pk_fma_f32 v[120:121], v[140:141], v[128:129], v[120:121]
	v_pk_fma_f32 v[124:125], v[144:145], v[124:125], v[156:157]
	v_pk_fma_f32 v[122:123], v[142:143], v[122:123], v[154:155]
	v_pk_fma_f32 v[128:129], v[136:137], v[174:175], v[158:159]
	v_pk_fma_f32 v[126:127], v[134:135], v[172:173], v[164:165]
	v_pk_fma_f32 v[116:117], v[132:133], v[116:117], v[160:161]
	v_pk_fma_f32 v[114:115], v[130:131], v[114:115], v[176:177]
	v_add_u32_e32 v154, 32, v150
	v_add_u32_e32 v247, 0x18000, v246
	global_load_dwordx2 v[216:217], v247, s[94:95] nt
	global_load_dwordx2 v[218:219], v247, s[94:95] offset:32 nt
	global_load_dwordx2 v[220:221], v247, s[94:95] offset:256 nt
	global_load_dwordx2 v[222:223], v247, s[94:95] offset:288 nt
	ds_read_b64 v[166:167], v183 offset:8320
	v_ashrrev_i32_e32 v155, 31, v154
	v_lshlrev_b64 v[172:173], 11, v[154:155]
	v_lshl_add_u64 v[172:173], s[94:95], 0, v[172:173]
	v_lshl_add_u64 v[172:173], v[172:173], 0, v[168:169]
	s_waitcnt lgkmcnt(0)
	v_pk_mul_f32 v[110:111], v[110:111], v[166:167] op_sel:[0,1]
	v_pk_mul_f32 v[112:113], v[112:113], v[166:167] op_sel:[0,1]
	v_pk_mul_f32 v[106:107], v[106:107], v[166:167] op_sel:[0,1]
	v_pk_mul_f32 v[108:109], v[108:109], v[166:167] op_sel:[0,1]
	v_pk_mul_f32 v[102:103], v[102:103], v[166:167] op_sel:[0,1]
	v_pk_mul_f32 v[104:105], v[104:105], v[166:167] op_sel:[0,1]
	v_pk_mul_f32 v[98:99], v[98:99], v[166:167] op_sel:[0,1]
	v_pk_mul_f32 v[100:101], v[100:101], v[166:167] op_sel:[0,1]
	v_add_f32_e32 v193, v126, v127
	v_add_f32_e32 v197, v128, v129
	v_mov_b32_e32 v192, v114
	v_mov_b32_e32 v196, v115
	v_mov_b32_e32 v198, v117
	s_waitcnt vmcnt(11)
	v_lshlrev_b32_e32 v166, 16, v224
	v_and_b32_e32 v167, 0xffff0000, v224
	v_lshlrev_b32_e32 v156, 16, v225
	v_and_b32_e32 v157, 0xffff0000, v225
	s_waitcnt vmcnt(10)
	v_lshlrev_b32_e32 v174, 16, v232
	v_and_b32_e32 v175, 0xffff0000, v232
	v_lshlrev_b32_e32 v158, 16, v233
	v_and_b32_e32 v159, 0xffff0000, v233
	s_waitcnt vmcnt(9)
	v_lshlrev_b32_e32 v176, 16, v234
	v_and_b32_e32 v177, 0xffff0000, v234
	v_lshlrev_b32_e32 v160, 16, v235
	v_and_b32_e32 v161, 0xffff0000, v235
	s_waitcnt vmcnt(8)
	v_lshlrev_b32_e32 v178, 16, v236
	v_and_b32_e32 v179, 0xffff0000, v236
	v_lshlrev_b32_e32 v164, 16, v237
	v_and_b32_e32 v165, 0xffff0000, v237
	v_pk_fma_f32 v[112:113], v[140:141], v[112:113], v[156:157]
	v_pk_fma_f32 v[110:111], v[138:139], v[110:111], v[166:167]
	v_pk_fma_f32 v[108:109], v[144:145], v[108:109], v[158:159]
	v_pk_fma_f32 v[106:107], v[142:143], v[106:107], v[174:175]
	v_pk_fma_f32 v[104:105], v[136:137], v[104:105], v[160:161]
	v_pk_fma_f32 v[102:103], v[134:135], v[102:103], v[176:177]
	v_pk_fma_f32 v[100:101], v[132:133], v[100:101], v[164:165]
	v_pk_fma_f32 v[98:99], v[130:131], v[98:99], v[178:179]
	v_add_u32_e32 v156, 48, v150
	v_add_u32_e32 v247, 0x40000, v246
	global_load_dwordx2 v[224:225], v247, s[94:95] nt
	global_load_dwordx2 v[232:233], v247, s[94:95] offset:32 nt
	global_load_dwordx2 v[234:235], v247, s[94:95] offset:256 nt
	global_load_dwordx2 v[236:237], v247, s[94:95] offset:288 nt
	ds_read_b64 v[172:173], v183 offset:8448
	v_ashrrev_i32_e32 v157, 31, v156
	v_lshlrev_b64 v[174:175], 11, v[156:157]
	v_lshl_add_u64 v[174:175], s[94:95], 0, v[174:175]
	v_lshl_add_u64 v[174:175], v[174:175], 0, v[168:169]
	s_waitcnt lgkmcnt(0)
	v_pk_mul_f32 v[94:95], v[94:95], v[172:173] op_sel:[0,1]
	v_pk_mul_f32 v[96:97], v[96:97], v[172:173] op_sel:[0,1]
	v_pk_mul_f32 v[90:91], v[90:91], v[172:173] op_sel:[0,1]
	v_pk_mul_f32 v[92:93], v[92:93], v[172:173] op_sel:[0,1]
	v_pk_mul_f32 v[86:87], v[86:87], v[172:173] op_sel:[0,1]
	v_pk_mul_f32 v[88:89], v[88:89], v[172:173] op_sel:[0,1]
	v_pk_mul_f32 v[82:83], v[82:83], v[172:173] op_sel:[0,1]
	v_pk_mul_f32 v[84:85], v[84:85], v[172:173] op_sel:[0,1]
	s_waitcnt vmcnt(11)
	v_lshlrev_b32_e32 v172, 16, v238
	v_and_b32_e32 v173, 0xffff0000, v238
	v_lshlrev_b32_e32 v158, 16, v239
	v_and_b32_e32 v159, 0xffff0000, v239
	s_waitcnt vmcnt(10)
	v_lshlrev_b32_e32 v176, 16, v240
	v_and_b32_e32 v177, 0xffff0000, v240
	v_lshlrev_b32_e32 v160, 16, v241
	v_and_b32_e32 v161, 0xffff0000, v241
	s_waitcnt vmcnt(9)
	v_lshlrev_b32_e32 v178, 16, v242
	v_and_b32_e32 v179, 0xffff0000, v242
	v_lshlrev_b32_e32 v164, 16, v243
	v_and_b32_e32 v165, 0xffff0000, v243
	s_waitcnt vmcnt(8)
	v_lshlrev_b32_e32 v180, 16, v244
	v_and_b32_e32 v181, 0xffff0000, v244
	v_lshlrev_b32_e32 v166, 16, v245
	v_and_b32_e32 v167, 0xffff0000, v245
	v_pk_fma_f32 v[96:97], v[140:141], v[96:97], v[158:159]
	v_pk_fma_f32 v[94:95], v[138:139], v[94:95], v[172:173]
	v_pk_fma_f32 v[92:93], v[144:145], v[92:93], v[160:161]
	v_pk_fma_f32 v[90:91], v[142:143], v[90:91], v[176:177]
	v_pk_fma_f32 v[88:89], v[136:137], v[88:89], v[164:165]
	v_pk_fma_f32 v[86:87], v[134:135], v[86:87], v[178:179]
	v_pk_fma_f32 v[84:85], v[132:133], v[84:85], v[166:167]
	v_pk_fma_f32 v[82:83], v[130:131], v[82:83], v[180:181]
	v_add_u32_e32 v158, 0x80, v150
	v_add_u32_e32 v247, 0x48000, v246
	global_load_dwordx2 v[238:239], v247, s[94:95] nt
	global_load_dwordx2 v[240:241], v247, s[94:95] offset:32 nt
	global_load_dwordx2 v[242:243], v247, s[94:95] offset:256 nt
	global_load_dwordx2 v[244:245], v247, s[94:95] offset:288 nt
	ds_read_b64 v[174:175], v183 offset:8576
	v_ashrrev_i32_e32 v159, 31, v158
	v_lshlrev_b64 v[176:177], 11, v[158:159]
	v_lshl_add_u64 v[176:177], s[94:95], 0, v[176:177]
	v_lshl_add_u64 v[176:177], v[176:177], 0, v[168:169]
	s_waitcnt lgkmcnt(0)
	v_pk_mul_f32 v[78:79], v[78:79], v[174:175] op_sel:[0,1]
	v_pk_mul_f32 v[80:81], v[80:81], v[174:175] op_sel:[0,1]
	v_pk_mul_f32 v[74:75], v[74:75], v[174:175] op_sel:[0,1]
	v_pk_mul_f32 v[76:77], v[76:77], v[174:175] op_sel:[0,1]
	v_pk_mul_f32 v[70:71], v[70:71], v[174:175] op_sel:[0,1]
	v_pk_mul_f32 v[72:73], v[72:73], v[174:175] op_sel:[0,1]
	v_pk_mul_f32 v[66:67], v[66:67], v[174:175] op_sel:[0,1]
	v_pk_mul_f32 v[68:69], v[68:69], v[174:175] op_sel:[0,1]
	s_waitcnt vmcnt(11)
	v_lshlrev_b32_e32 v174, 16, v216
	v_and_b32_e32 v175, 0xffff0000, v216
	v_lshlrev_b32_e32 v160, 16, v217
	v_and_b32_e32 v161, 0xffff0000, v217
	s_waitcnt vmcnt(10)
	v_lshlrev_b32_e32 v178, 16, v218
	v_and_b32_e32 v179, 0xffff0000, v218
	v_lshlrev_b32_e32 v164, 16, v219
	v_and_b32_e32 v165, 0xffff0000, v219
	s_waitcnt vmcnt(9)
	v_lshlrev_b32_e32 v180, 16, v220
	v_and_b32_e32 v181, 0xffff0000, v220
	v_lshlrev_b32_e32 v166, 16, v221
	v_and_b32_e32 v167, 0xffff0000, v221
	s_waitcnt vmcnt(8)
	v_lshlrev_b32_e32 v186, 16, v222
	v_and_b32_e32 v187, 0xffff0000, v222
	v_lshlrev_b32_e32 v172, 16, v223
	v_and_b32_e32 v173, 0xffff0000, v223
	v_pk_fma_f32 v[80:81], v[140:141], v[80:81], v[160:161]
	v_pk_fma_f32 v[78:79], v[138:139], v[78:79], v[174:175]
	v_pk_fma_f32 v[76:77], v[144:145], v[76:77], v[164:165]
	v_pk_fma_f32 v[74:75], v[142:143], v[74:75], v[178:179]
	v_pk_fma_f32 v[72:73], v[136:137], v[72:73], v[166:167]
	v_pk_fma_f32 v[70:71], v[134:135], v[70:71], v[180:181]
	v_pk_fma_f32 v[68:69], v[132:133], v[68:69], v[172:173]
	v_pk_fma_f32 v[66:67], v[130:131], v[66:67], v[186:187]
	v_add_u32_e32 v160, 0x90, v150
	v_add_u32_e32 v247, 0x50000, v246
	global_load_dwordx2 v[216:217], v247, s[94:95] nt
	global_load_dwordx2 v[218:219], v247, s[94:95] offset:32 nt
	global_load_dwordx2 v[220:221], v247, s[94:95] offset:256 nt
	global_load_dwordx2 v[222:223], v247, s[94:95] offset:288 nt
	ds_read_b64 v[176:177], v183 offset:9216
	v_ashrrev_i32_e32 v161, 31, v160
	v_lshlrev_b64 v[178:179], 11, v[160:161]
	v_lshl_add_u64 v[178:179], s[94:95], 0, v[178:179]
	v_lshl_add_u64 v[178:179], v[178:179], 0, v[168:169]
	s_waitcnt lgkmcnt(0)
	v_pk_mul_f32 v[62:63], v[62:63], v[176:177] op_sel:[0,1]
	v_pk_mul_f32 v[64:65], v[64:65], v[176:177] op_sel:[0,1]
	v_pk_mul_f32 v[58:59], v[58:59], v[176:177] op_sel:[0,1]
	v_pk_mul_f32 v[60:61], v[60:61], v[176:177] op_sel:[0,1]
	v_pk_mul_f32 v[54:55], v[54:55], v[176:177] op_sel:[0,1]
	v_pk_mul_f32 v[56:57], v[56:57], v[176:177] op_sel:[0,1]
	v_pk_mul_f32 v[50:51], v[50:51], v[176:177] op_sel:[0,1]
	v_pk_mul_f32 v[52:53], v[52:53], v[176:177] op_sel:[0,1]
	s_waitcnt vmcnt(11)
	v_lshlrev_b32_e32 v176, 16, v224
	v_and_b32_e32 v177, 0xffff0000, v224
	v_lshlrev_b32_e32 v164, 16, v225
	v_and_b32_e32 v165, 0xffff0000, v225
	s_waitcnt vmcnt(10)
	v_lshlrev_b32_e32 v180, 16, v232
	v_and_b32_e32 v181, 0xffff0000, v232
	v_lshlrev_b32_e32 v166, 16, v233
	v_and_b32_e32 v167, 0xffff0000, v233
	s_waitcnt vmcnt(9)
	v_lshlrev_b32_e32 v186, 16, v234
	v_and_b32_e32 v187, 0xffff0000, v234
	v_lshlrev_b32_e32 v172, 16, v235
	v_and_b32_e32 v173, 0xffff0000, v235
	s_waitcnt vmcnt(8)
	v_lshlrev_b32_e32 v188, 16, v236
	v_and_b32_e32 v189, 0xffff0000, v236
	v_lshlrev_b32_e32 v174, 16, v237
	v_and_b32_e32 v175, 0xffff0000, v237
	v_pk_fma_f32 v[64:65], v[140:141], v[64:65], v[164:165]
	v_pk_fma_f32 v[62:63], v[138:139], v[62:63], v[176:177]
	v_pk_fma_f32 v[60:61], v[144:145], v[60:61], v[166:167]
	v_pk_fma_f32 v[58:59], v[142:143], v[58:59], v[180:181]
	v_pk_fma_f32 v[56:57], v[136:137], v[56:57], v[172:173]
	v_pk_fma_f32 v[54:55], v[134:135], v[54:55], v[186:187]
	v_pk_fma_f32 v[52:53], v[132:133], v[52:53], v[174:175]
	v_pk_fma_f32 v[50:51], v[130:131], v[50:51], v[188:189]
	v_add_u32_e32 v164, 0xa0, v150
	v_add_u32_e32 v247, 0x58000, v246
	global_load_dwordx2 v[224:225], v247, s[94:95] nt
	global_load_dwordx2 v[232:233], v247, s[94:95] offset:32 nt
	global_load_dwordx2 v[234:235], v247, s[94:95] offset:256 nt
	global_load_dwordx2 v[236:237], v247, s[94:95] offset:288 nt
	ds_read_b64 v[178:179], v183 offset:9344
	v_ashrrev_i32_e32 v165, 31, v164
	v_lshlrev_b64 v[180:181], 11, v[164:165]
	v_lshl_add_u64 v[180:181], s[94:95], 0, v[180:181]
	v_lshl_add_u64 v[180:181], v[180:181], 0, v[168:169]
	s_waitcnt lgkmcnt(0)
	v_pk_mul_f32 v[46:47], v[46:47], v[178:179] op_sel:[0,1]
	v_pk_mul_f32 v[48:49], v[48:49], v[178:179] op_sel:[0,1]
	v_pk_mul_f32 v[42:43], v[42:43], v[178:179] op_sel:[0,1]
	v_pk_mul_f32 v[44:45], v[44:45], v[178:179] op_sel:[0,1]
	v_pk_mul_f32 v[38:39], v[38:39], v[178:179] op_sel:[0,1]
	v_pk_mul_f32 v[40:41], v[40:41], v[178:179] op_sel:[0,1]
	v_pk_mul_f32 v[34:35], v[34:35], v[178:179] op_sel:[0,1]
	v_pk_mul_f32 v[36:37], v[36:37], v[178:179] op_sel:[0,1]
	s_waitcnt vmcnt(11)
	v_lshlrev_b32_e32 v178, 16, v238
	v_and_b32_e32 v179, 0xffff0000, v238
	v_lshlrev_b32_e32 v166, 16, v239
	v_and_b32_e32 v167, 0xffff0000, v239
	s_waitcnt vmcnt(10)
	v_lshlrev_b32_e32 v186, 16, v240
	v_and_b32_e32 v187, 0xffff0000, v240
	v_lshlrev_b32_e32 v172, 16, v241
	v_and_b32_e32 v173, 0xffff0000, v241
	s_waitcnt vmcnt(9)
	v_lshlrev_b32_e32 v188, 16, v242
	v_and_b32_e32 v189, 0xffff0000, v242
	v_lshlrev_b32_e32 v174, 16, v243
	v_and_b32_e32 v175, 0xffff0000, v243
	s_waitcnt vmcnt(8)
	v_lshlrev_b32_e32 v190, 16, v244
	v_and_b32_e32 v191, 0xffff0000, v244
	v_lshlrev_b32_e32 v176, 16, v245
	v_and_b32_e32 v177, 0xffff0000, v245
	v_pk_fma_f32 v[48:49], v[140:141], v[48:49], v[166:167]
	v_pk_fma_f32 v[46:47], v[138:139], v[46:47], v[178:179]
	v_pk_fma_f32 v[44:45], v[144:145], v[44:45], v[172:173]
	v_pk_fma_f32 v[42:43], v[142:143], v[42:43], v[186:187]
	v_pk_fma_f32 v[40:41], v[136:137], v[40:41], v[174:175]
	v_pk_fma_f32 v[38:39], v[134:135], v[38:39], v[188:189]
	v_pk_fma_f32 v[36:37], v[132:133], v[36:37], v[176:177]
	v_pk_fma_f32 v[34:35], v[130:131], v[34:35], v[190:191]
	v_add_u32_e32 v166, 0xb0, v150
	ds_read_b64 v[194:195], v183 offset:9472
	v_ashrrev_i32_e32 v167, 31, v166
	v_lshlrev_b64 v[180:181], 11, v[166:167]
	v_lshl_add_u64 v[180:181], s[94:95], 0, v[180:181]
	v_lshl_add_u64 v[168:169], v[180:181], 0, v[168:169]
	s_waitcnt lgkmcnt(0)
	v_mul_f32_e32 v30, v30, v195
	v_mul_f32_e32 v31, v31, v195
	v_mul_f32_e32 v32, v32, v195
	v_mul_f32_e32 v33, v33, v195
	v_mul_f32_e32 v26, v26, v195
	v_mul_f32_e32 v27, v27, v195
	v_mul_f32_e32 v28, v28, v195
	v_mul_f32_e32 v29, v29, v195
	v_mul_f32_e32 v22, v22, v195
	v_mul_f32_e32 v23, v23, v195
	v_mul_f32_e32 v24, v24, v195
	v_mul_f32_e32 v25, v25, v195
	v_mul_f32_e32 v18, v18, v195
	v_mul_f32_e32 v19, v19, v195
	v_mul_f32_e32 v20, v20, v195
	v_mul_f32_e32 v21, v21, v195
	s_waitcnt vmcnt(7)
	v_lshlrev_b32_e32 v194, 16, v216
	v_and_b32_e32 v195, 0xffff0000, v216
	v_lshlrev_b32_e32 v172, 16, v217
	v_and_b32_e32 v173, 0xffff0000, v217
	s_waitcnt vmcnt(5)
	v_lshlrev_b32_e32 v204, 16, v220
	v_and_b32_e32 v205, 0xffff0000, v220
	v_lshlrev_b32_e32 v176, 16, v221
	v_and_b32_e32 v177, 0xffff0000, v221
	v_pk_fma_f32 v[32:33], v[140:141], v[32:33], v[172:173]
	v_pk_fma_f32 v[24:25], v[136:137], v[24:25], v[176:177]
	v_add_f32_e32 v172, v119, v118
	v_add_f32_e32 v173, v120, v121
	v_add_f32_e32 v176, v123, v122
	v_add_f32_e32 v177, v124, v125
	v_add_f32_e32 v186, v172, v173
	v_add_f32_e32 v172, v176, v176
	v_add_f32_e32 v173, v176, v177
	s_waitcnt vmcnt(6)
	v_lshlrev_b32_e32 v200, 16, v218
	v_and_b32_e32 v201, 0xffff0000, v218
	v_lshlrev_b32_e32 v174, 16, v219
	v_and_b32_e32 v175, 0xffff0000, v219
	s_waitcnt vmcnt(4)
	v_lshlrev_b32_e32 v206, 16, v222
	v_and_b32_e32 v207, 0xffff0000, v222
	v_lshlrev_b32_e32 v178, 16, v223
	v_and_b32_e32 v179, 0xffff0000, v223
	v_add_f32_e32 v199, 0, v186
	v_pk_fma_f32 v[30:31], v[138:139], v[30:31], v[194:195]
	v_pk_fma_f32 v[28:29], v[144:145], v[28:29], v[174:175]
	v_pk_fma_f32 v[26:27], v[142:143], v[26:27], v[200:201]
	v_pk_fma_f32 v[22:23], v[134:135], v[22:23], v[204:205]
	v_pk_fma_f32 v[20:21], v[132:133], v[20:21], v[178:179]
	v_pk_fma_f32 v[18:19], v[130:131], v[18:19], v[206:207]
	v_add_f32_e32 v178, v192, v196
	v_add_f32_e32 v179, v193, v197
	v_add_f32_e32 v172, v116, v198
	v_add_f32_e32 v173, v173, v199
	v_add_f32_e32 v172, v178, v172
	v_add_f32_e32 v173, v179, v173
	v_add_f32_e32 v168, v172, v173
	v_mov_b32_e32 v169, v168
	s_nop 1
	v_permlane16_swap_b32_e32 v168, v169
	s_waitcnt lgkmcnt(0)
	v_add_f32_e32 v168, v168, v169
	v_mov_b32_e32 v169, v168
	s_nop 1
	v_permlane32_swap_b32_e32 v168, v169
	s_waitcnt lgkmcnt(0)
	v_add_f32_e32 v168, v168, v169
	v_fmamk_f32 v172, v168, 0xbc800000, v121
	v_fmamk_f32 v186, v168, 0xbc800000, v119
	v_fmamk_f32 v188, v168, 0xbc800000, v125
	v_fmamk_f32 v190, v168, 0xbc800000, v123
	v_fmamk_f32 v169, v168, 0xbc800000, v120
	v_fmamk_f32 v173, v168, 0xbc800000, v118
	v_fmamk_f32 v187, v168, 0xbc800000, v124
	v_fmamk_f32 v189, v168, 0xbc800000, v122
	v_fmamk_f32 v192, v168, 0xbc800000, v129
	v_fmamk_f32 v194, v168, 0xbc800000, v127
	v_mul_f32_e32 v186, v186, v186
	v_mul_f32_e32 v172, v172, v172
	v_mul_f32_e32 v190, v190, v190
	v_mul_f32_e32 v188, v188, v188
	v_fmamk_f32 v191, v168, 0xbc800000, v128
	v_fmamk_f32 v193, v168, 0xbc800000, v126
	v_fmamk_f32 v196, v168, 0xbc800000, v117
	v_fmamk_f32 v198, v168, 0xbc800000, v115
	v_mul_f32_e32 v194, v194, v194
	v_mul_f32_e32 v192, v192, v192
	v_fmac_f32_e32 v186, v173, v173
	v_fmac_f32_e32 v172, v169, v169
	v_fmac_f32_e32 v190, v189, v189
	v_fmac_f32_e32 v188, v187, v187
	v_fmamk_f32 v195, v168, 0xbc800000, v116
	v_fmamk_f32 v197, v168, 0xbc800000, v114
	v_mul_f32_e32 v198, v198, v198
	v_mul_f32_e32 v196, v196, v196
	v_fmac_f32_e32 v194, v193, v193
	v_fmac_f32_e32 v192, v191, v191
	v_add_f32_e32 v169, v186, v172
	v_add_f32_e32 v172, v190, v188
	v_fmac_f32_e32 v198, v197, v197
	v_fmac_f32_e32 v196, v195, v195
	v_add_f32_e32 v173, v194, v192
	v_add_f32_e32 v169, v169, v172
	v_add_f32_e32 v186, v198, v196
	v_add_f32_e32 v169, v173, v169
	v_add_f32_e32 v169, v186, v169
	v_mov_b32_e32 v172, v169
	s_nop 1
	v_permlane16_swap_b32_e32 v169, v172
	ds_read_b64 v[186:187], v183 offset:9600
	s_waitcnt lgkmcnt(1)
	v_add_f32_e32 v169, v169, v172
	ds_bpermute_b32 v172, v202, v169
	s_waitcnt lgkmcnt(1)
	v_mul_f32_e32 v14, v14, v187
	v_mul_f32_e32 v15, v15, v187
	v_mul_f32_e32 v16, v16, v187
	v_mul_f32_e32 v17, v17, v187
	v_mul_f32_e32 v10, v10, v187
	v_mul_f32_e32 v11, v11, v187
	v_mul_f32_e32 v12, v12, v187
	v_mul_f32_e32 v13, v13, v187
	v_mul_f32_e32 v6, v6, v187
	v_mul_f32_e32 v7, v7, v187
	v_mul_f32_e32 v8, v8, v187
	v_mul_f32_e32 v9, v9, v187
	v_mul_f32_e32 v2, v2, v187
	v_mul_f32_e32 v3, v3, v187
	v_mul_f32_e32 v4, v4, v187
	v_mul_f32_e32 v5, v5, v187
	s_waitcnt vmcnt(3)
	v_lshlrev_b32_e32 v186, 16, v224
	v_and_b32_e32 v187, 0xffff0000, v224
	v_lshlrev_b32_e32 v174, 16, v225
	v_and_b32_e32 v175, 0xffff0000, v225
	s_waitcnt vmcnt(2)
	v_lshlrev_b32_e32 v188, 16, v232
	v_and_b32_e32 v189, 0xffff0000, v232
	v_lshlrev_b32_e32 v180, 16, v233
	v_and_b32_e32 v181, 0xffff0000, v233
	s_waitcnt vmcnt(1)
	v_lshlrev_b32_e32 v190, 16, v234
	v_and_b32_e32 v191, 0xffff0000, v234
	v_lshlrev_b32_e32 v176, 16, v235
	v_and_b32_e32 v177, 0xffff0000, v235
	s_waitcnt vmcnt(0)
	v_lshlrev_b32_e32 v192, 16, v236
	v_and_b32_e32 v193, 0xffff0000, v236
	v_lshlrev_b32_e32 v178, 16, v237
	v_and_b32_e32 v179, 0xffff0000, v237
	v_pk_fma_f32 v[16:17], v[140:141], v[16:17], v[174:175]
	v_pk_fma_f32 v[14:15], v[138:139], v[14:15], v[186:187]
	v_pk_fma_f32 v[12:13], v[144:145], v[12:13], v[180:181]
	v_pk_fma_f32 v[10:11], v[142:143], v[10:11], v[188:189]
	v_pk_fma_f32 v[8:9], v[136:137], v[8:9], v[176:177]
	v_pk_fma_f32 v[6:7], v[134:135], v[6:7], v[190:191]
	v_pk_fma_f32 v[4:5], v[132:133], v[4:5], v[178:179]
	v_pk_fma_f32 v[2:3], v[130:131], v[2:3], v[192:193]
	s_nop 0
	s_and_saveexec_b64 s[0:1], s[6:7]
	s_cbranch_execz .LBB0_1493
	s_lshl_b32 s19, s33, 11
	s_add_i32 s19, s17, s19
	v_mul_f32_e32 v130, 0x3c800000, v168
	s_waitcnt lgkmcnt(0)
	v_add_f32_e32 v131, v169, v172
	v_lshl_add_u32 v132, v170, 5, s19
	ds_write_b64 v132, v[130:131]

.LBB0_1678:
	s_lshl_b32 s16, s24, 8
	v_add_u32_e32 v249, s16, v149
	v_lshlrev_b32_e32 v249, 11, v249
	s_lshl_b32 s17, s8, 8
	s_lshl_b32 s18, s25, 5
	s_or_b32 s17, s17, s18
	v_lshrrev_b32_e32 v230, 2, v0
	v_and_or_b32 v230, v230, 12, s17
	v_lshl_add_u32 v248, v230, 1, v249
	s_lshl_b32 s19, s24, 5
	s_and_b32 s19, s19, 0xfffffc00
	s_lshl_b32 s19, s19, 2
	s_add_i32 s19, s19, 0x112000
	v_lshl_add_u32 v250, v230, 2, s19
	global_load_dwordx4 v[232:235], v250, s[34:35]
	global_load_dwordx4 v[236:239], v250, s[34:35] offset:64
	global_load_dwordx4 v[240:243], v250, s[34:35] offset:512
	global_load_dwordx4 v[244:247], v250, s[34:35] offset:576
	global_load_dwordx2 v[164:165], v248, s[56:57] nt
	global_load_dwordx2 v[166:167], v248, s[56:57] offset:32 nt
	global_load_dwordx2 v[168:169], v248, s[56:57] offset:256 nt
	global_load_dwordx2 v[170:171], v248, s[56:57] offset:288 nt
	v_add_u32_e32 v249, 0x8000, v248
	global_load_dwordx2 v[172:173], v249, s[56:57] nt
	global_load_dwordx2 v[174:175], v249, s[56:57] offset:32 nt
	global_load_dwordx2 v[176:177], v249, s[56:57] offset:256 nt
	global_load_dwordx2 v[178:179], v249, s[56:57] offset:288 nt
	v_add_u32_e32 v249, 0x10000, v248
	global_load_dwordx2 v[180:181], v249, s[56:57] nt
	global_load_dwordx2 v[182:183], v249, s[56:57] offset:32 nt
	global_load_dwordx2 v[184:185], v249, s[56:57] offset:256 nt
	global_load_dwordx2 v[186:187], v249, s[56:57] offset:288 nt
	v_add_u32_e32 v249, 0x18000, v248
	global_load_dwordx2 v[188:189], v249, s[56:57] nt
	global_load_dwordx2 v[190:191], v249, s[56:57] offset:32 nt
	global_load_dwordx2 v[192:193], v249, s[56:57] offset:256 nt
	global_load_dwordx2 v[194:195], v249, s[56:57] offset:288 nt
	v_add_u32_e32 v249, 0x40000, v248
	global_load_dwordx2 v[196:197], v249, s[56:57] nt
	global_load_dwordx2 v[198:199], v249, s[56:57] offset:32 nt
	global_load_dwordx2 v[200:201], v249, s[56:57] offset:256 nt
	global_load_dwordx2 v[204:205], v249, s[56:57] offset:288 nt
	v_add_u32_e32 v249, 0x48000, v248
	global_load_dwordx2 v[206:207], v249, s[56:57] nt
	global_load_dwordx2 v[208:209], v249, s[56:57] offset:32 nt
	global_load_dwordx2 v[210:211], v249, s[56:57] offset:256 nt
	global_load_dwordx2 v[212:213], v249, s[56:57] offset:288 nt
	v_add_u32_e32 v249, 0x50000, v248
	global_load_dwordx2 v[214:215], v249, s[56:57] nt
	global_load_dwordx2 v[216:217], v249, s[56:57] offset:32 nt
	global_load_dwordx2 v[218:219], v249, s[56:57] offset:256 nt
	global_load_dwordx2 v[220:221], v249, s[56:57] offset:288 nt
	v_add_u32_e32 v249, 0x58000, v248
	global_load_dwordx2 v[222:223], v249, s[56:57] nt
	global_load_dwordx2 v[224:225], v249, s[56:57] offset:32 nt
	global_load_dwordx2 v[226:227], v249, s[56:57] offset:256 nt
	global_load_dwordx2 v[228:229], v249, s[56:57] offset:288 nt
	v_add_f32_e32 v130, v127, v126
	v_add_f32_e32 v131, v128, v129
	v_add_f32_e32 v132, v123, v122
	v_add_f32_e32 v133, v124, v125
	v_add_f32_e32 v130, v130, v131
	v_add_f32_e32 v133, v132, v133
	v_add_f32_e32 v132, v132, v132
	v_add_f32_e32 v131, 0, v130
	v_add_f32_e32 v135, v118, v119
	v_add_f32_e32 v137, v120, v121
	v_mov_b32_e32 v136, v111
	v_add_f32_e32 v134, v110, v111
	v_add_f32_e32 v135, v135, v137
	v_add_f32_e32 v130, v112, v113
	v_add_f32_e32 v131, v133, v131
	v_add_f32_e32 v130, v134, v130
	v_add_f32_e32 v131, v135, v131
	v_add_f32_e32 v130, v130, v131
	v_mov_b32_e32 v131, v130
	s_nop 1
	v_permlane16_swap_b32_e32 v130, v131
	s_lshl_b32 s0, s25, 3
	s_add_i32 s2, s0, 0
	s_barrier
	s_waitcnt lgkmcnt(0)
	v_add_f32_e32 v130, v130, v131
	v_mov_b32_e32 v131, v130
	s_nop 1
	v_permlane32_swap_b32_e32 v130, v131
	s_waitcnt lgkmcnt(0)
	v_add_f32_e32 v131, v130, v131
	v_fmamk_f32 v132, v131, 0xbc800000, v129
	v_fmamk_f32 v134, v131, 0xbc800000, v127
	v_fmamk_f32 v130, v131, 0xbc800000, v128
	v_fmamk_f32 v133, v131, 0xbc800000, v126
	v_mul_f32_e32 v134, v134, v134
	v_mul_f32_e32 v132, v132, v132
	v_fmac_f32_e32 v134, v133, v133
	v_fmac_f32_e32 v132, v130, v130
	v_add_f32_e32 v130, v134, v132
	v_fmamk_f32 v133, v131, 0xbc800000, v125
	v_fmamk_f32 v135, v131, 0xbc800000, v123
	v_fmamk_f32 v132, v131, 0xbc800000, v124
	v_fmamk_f32 v134, v131, 0xbc800000, v122
	v_mul_f32_e32 v135, v135, v135
	v_mul_f32_e32 v133, v133, v133
	v_fmac_f32_e32 v135, v134, v134
	v_fmac_f32_e32 v133, v132, v132
	v_add_f32_e32 v132, v135, v133
	v_fmamk_f32 v133, v131, 0xbc800000, v121
	v_fmamk_f32 v135, v131, 0xbc800000, v119
	v_add_f32_e32 v130, v130, v132
	v_fmamk_f32 v132, v131, 0xbc800000, v120
	v_fmamk_f32 v134, v131, 0xbc800000, v118
	v_mul_f32_e32 v135, v135, v135
	v_mul_f32_e32 v133, v133, v133
	v_fmac_f32_e32 v135, v134, v134
	v_fmac_f32_e32 v133, v132, v132
	v_add_f32_e32 v132, v135, v133
	v_fmamk_f32 v133, v131, 0xbc800000, v113
	v_fmamk_f32 v135, v131, 0xbc800000, v111
	v_add_f32_e32 v130, v132, v130
	v_fmamk_f32 v132, v131, 0xbc800000, v112
	v_fmamk_f32 v134, v131, 0xbc800000, v110
	v_mul_f32_e32 v135, v135, v135
	v_mul_f32_e32 v133, v133, v133
	v_fmac_f32_e32 v135, v134, v134
	v_fmac_f32_e32 v133, v132, v132
	v_add_f32_e32 v132, v135, v133
	v_add_f32_e32 v132, v132, v130
	v_mov_b32_e32 v133, v132
	s_nop 1
	v_permlane16_swap_b32_e32 v132, v133
	v_and_b32_e32 v130, 63, v0
	v_cmp_gt_u32_e32 vcc, 16, v130
	s_waitcnt lgkmcnt(0)
	v_add_f32_e32 v132, v132, v133
	v_mov_b32_e32 v133, v132
	s_nop 1
	v_permlane32_swap_b32_e32 v132, v133
	s_and_saveexec_b64 s[0:1], vcc
	s_cbranch_execz .LBB0_1680
	s_lshl_b32 s3, s27, 11
	s_add_i32 s3, s2, s3
	v_mul_f32_e32 v134, 0x3c800000, v131
	s_waitcnt lgkmcnt(0)
	v_add_f32_e32 v135, v132, v133
	v_lshl_add_u32 v131, v146, 5, s3
	ds_write_b64 v131, v[134:135]
